# per-workgroup start skew (0-7 x s_sleep 5 by blockIdx/8) at the start of the four big GEMM phases so CUs of an XCD do not walk K in lockstep on the same L2 channels
# baseline (speedup 1.0000x reference)
.LBB0_167:
	s_cmp_lt_i32 s76, 3
	s_cselect_b64 s[0:1], -1, 0
	s_cmp_gt_i32 s77, 2
	s_cselect_b64 s[2:3], -1, 0
	s_and_b64 s[0:1], s[0:1], s[2:3]
	s_andn2_b64 vcc, exec, s[0:1]
	s_cbranch_vccnz .LBB0_270
	s_lshr_b32 s99, s30, 3
	s_and_b32 s99, s99, 7
.Lskew_p2_loop:
	s_cmp_eq_u32 s99, 0
	s_cbranch_scc1 .Lskew_p2_done
	s_sleep 5
	s_sub_u32 s99, s99, 1
	s_branch .Lskew_p2_loop
.Lskew_p2_done:
	s_cmpk_gt_i32 s30, 0x68f
	v_readfirstlane_b32 s3, v0
	s_cbranch_scc1 .LBB0_190
	v_lshrrev_b32_e32 v2, 5, v0
	v_lshrrev_b32_e32 v4, 1, v0
	v_and_b32_e32 v2, 4, v2
	v_bfe_u32 v3, v0, 2, 2
	v_and_b32_e32 v13, 24, v4
	s_add_u32 s28, s74, 0x6c00000
	v_or3_b32 v2, v2, v3, v13
	v_lshlrev_b32_e32 v3, 4, v0
	s_addc_u32 s29, s75, 0
	v_or_b32_e32 v10, 0x2000, v3
	s_add_u32 s31, s74, 0xc00000
	v_lshrrev_b32_e32 v4, 7, v10
	s_movk_i32 s0, 0x60
	s_addc_u32 s40, s75, 0
	v_and_or_b32 v5, v4, s0, v2
	v_bfe_u32 v14, v0, 2, 4
	s_movk_i32 s0, 0x70
	s_ashr_i32 s42, s30, 31
	v_and_or_b32 v4, v4, s0, v14
	s_lshr_b32 s0, s42, 29
	s_add_i32 s0, s30, s0
	s_lshr_b32 s6, s3, 6
	s_ashr_i32 s1, s0, 3
	s_and_b32 s0, s0, -8
	s_lshr_b32 s8, s3, 8
	s_lshl_b32 s41, s6, 10
	s_sub_i32 s0, s30, s0
	s_cmp_lt_i32 s0, 0
	s_movk_i32 s43, 0xd3
	s_cselect_b32 s2, s43, 0xd2
	s_mul_i32 s0, s0, s2
	s_add_i32 s0, s0, s1
	s_mul_hi_i32 s1, s0, 0x30c30c31
	s_lshr_b32 s2, s1, 31
	s_ashr_i32 s1, s1, 5
	s_add_i32 s1, s1, s2
	s_lshl_b32 s4, s1, 3
	s_mulk_i32 s1, 0xa8
	s_sub_i32 s0, s0, s1
	s_sext_i32_i16 s1, s0
	s_bfe_u32 s1, s1, 0x3001c
	s_add_i32 s1, s0, s1
	s_sext_i32_i16 s2, s1
	s_and_b32 s1, s1, 0xfff8
	s_sub_i32 s0, s0, s1
	s_sext_i32_i16 s0, s0
	v_and_b32_e32 v6, 32, v0
	s_lshr_b32 s2, s2, 3
	s_add_i32 s20, s4, s0
	v_bitop3_b32 v11, v3, v6, 48 bitop3:0x6c
	v_and_b32_e32 v12, 64, v0
	s_ashr_i32 s21, s20, 31
	s_bfe_i64 s[4:5], s[2:3], 0x100000
	v_or_b32_e32 v3, v11, v12
	s_lshl_b64 s[0:1], s[20:21], 20
	s_lshl_b64 s[4:5], s[4:5], 20
	v_lshl_or_b32 v132, v4, 12, v3
	v_lshrrev_b32_e32 v4, 3, v0
	s_add_u32 s24, s31, s4
	v_and_or_b32 v2, v4, 32, v2
	s_addc_u32 s25, s40, s5
	s_add_i32 s46, s41, 0
	v_lshl_or_b32 v134, v2, 12, v3
	s_add_i32 m0, s46, 0x10000
	v_lshl_or_b32 v130, v5, 12, v3
	global_load_lds_dwordx4 v134, s[24:25]
	s_add_i32 m0, s46, 0x12000
	s_add_u32 s4, s24, 0x80000
	global_load_lds_dwordx4 v130, s[24:25]
	s_addc_u32 s5, s25, 0
	s_add_i32 m0, s46, 0x14000
	v_and_or_b32 v2, v4, 48, v14
	global_load_lds_dwordx4 v134, s[4:5]
	s_add_i32 m0, s46, 0x16000
	s_add_u32 s22, s28, s0
	s_addc_u32 s23, s29, s1
	s_add_i32 s47, s46, 0x2000
	v_lshl_or_b32 v136, v2, 12, v3
	global_load_lds_dwordx4 v130, s[4:5]
	s_mov_b32 m0, s46
	s_add_u32 s0, s22, 0x80000
	global_load_lds_dwordx4 v136, s[22:23]
	s_mov_b32 m0, s47
	s_addc_u32 s1, s23, 0
	s_add_i32 s48, s46, 0x4000
	global_load_lds_dwordx4 v132, s[22:23]
	s_mov_b32 m0, s48
	s_add_i32 s49, s46, 0x6000
	global_load_lds_dwordx4 v136, s[0:1]
	s_mov_b32 m0, s49
	v_mov_b32_e32 v135, 0
	global_load_lds_dwordx4 v132, s[0:1]
	v_mov_b32_e32 v131, v135
	v_mov_b32_e32 v137, v135
	v_mov_b32_e32 v133, v135
	s_cmp_eq_u32 s8, 1
	s_mov_b32 s56, 0
	v_lshl_add_u64 v[8:9], s[24:25], 0, v[134:135]
	v_lshl_add_u64 v[6:7], s[24:25], 0, v[130:131]
	v_lshl_add_u64 v[2:3], s[22:23], 0, v[136:137]
	s_cselect_b64 s[0:1], -1, 0
	s_cmp_lg_u32 s8, 1
	v_lshl_add_u64 v[4:5], s[22:23], 0, v[132:133]
	s_cbranch_scc1 .LBB0_171
	s_barrier

.LBB0_564:
	s_cmp_lt_i32 s76, 6
	s_cselect_b64 s[0:1], -1, 0
	s_cmp_gt_i32 s77, 5
	s_cselect_b64 s[2:3], -1, 0
	s_and_b64 s[0:1], s[0:1], s[2:3]
	s_andn2_b64 vcc, exec, s[0:1]
	s_cbranch_vccnz .LBB0_664
	s_lshr_b32 s99, s30, 3
	s_and_b32 s99, s99, 7

.Lskew_p5_done:
	s_cmpk_lt_i32 s30, 0x200
	s_cselect_b64 s[0:1], -1, 0
	s_cmpk_gt_i32 s30, 0x1ff
	s_mov_b32 s28, 0
	s_cbranch_scc1 .LBB0_567
	s_abs_i32 s2, s33
	v_cvt_f32_u32_e32 v1, s2
	s_sub_i32 s3, s33, s30
	s_add_i32 s4, s3, 0x1ff
	s_sub_i32 s3, 0xfffffe01, s3
	v_rcp_iflag_f32_e32 v1, v1
	s_xor_b32 s6, s4, s33
	s_sub_i32 s5, 0, s2
	s_max_i32 s3, s4, s3
	v_mul_f32_e32 v1, 0x4f7ffffe, v1
	v_cvt_u32_f32_e32 v1, v1
	s_ashr_i32 s4, s6, 31
	v_readfirstlane_b32 s6, v1
	s_mul_i32 s5, s5, s6
	s_mul_hi_u32 s5, s6, s5
	s_add_i32 s6, s6, s5
	s_mul_hi_u32 s5, s3, s6
	s_mul_i32 s6, s5, s2
	s_sub_i32 s3, s3, s6
	s_add_i32 s7, s5, 1
	s_sub_i32 s6, s3, s2
	s_cmp_ge_u32 s3, s2
	s_cselect_b32 s5, s7, s5
	s_cselect_b32 s3, s6, s3
	s_add_i32 s6, s5, 1
	s_cmp_ge_u32 s3, s2
	s_cselect_b32 s2, s6, s5
	s_xor_b32 s2, s2, s4
	s_sub_i32 s28, s2, s4

.LBB0_729:
	s_cmp_lt_i32 s76, 8
	s_cselect_b64 s[0:1], -1, 0
	s_cmp_gt_i32 s77, 7
	s_cselect_b64 s[2:3], -1, 0
	s_and_b64 s[0:1], s[0:1], s[2:3]
	s_andn2_b64 vcc, exec, s[0:1]
	s_cbranch_vccnz .LBB0_800
	s_lshr_b32 s99, s30, 3
	s_and_b32 s99, s99, 7

.Lskew_p7_done:
	s_cmpk_gt_i32 s30, 0x9ff
	v_readfirstlane_b32 s2, v0
	s_cbranch_scc1 .LBB0_746
	s_add_u32 s28, s74, 0x6c00000
	v_lshlrev_b32_e32 v1, 4, v0
	v_lshrrev_b32_e32 v6, 5, v0
	s_addc_u32 s29, s75, 0
	v_and_b32_e32 v154, 48, v0
	s_waitcnt vmcnt(0)
	v_or_b32_e32 v10, 0x2000, v1
	v_bfe_u32 v5, v0, 2, 2
	v_and_b32_e32 v6, 4, v6
	s_add_u32 s31, s74, 0x2900000
	v_lshrrev_b32_e32 v3, 6, v10
	v_or3_b32 v5, v5, v6, v154
	s_movk_i32 s0, 0xc0
	s_addc_u32 s36, s75, 0
	v_lshrrev_b32_e32 v2, 7, v10
	v_and_or_b32 v3, v3, s0, v5
	v_bfe_u32 v13, v0, 2, 4
	s_movk_i32 s0, 0x70
	s_ashr_i32 s38, s30, 31
	v_and_or_b32 v2, v2, s0, v13
	s_lshr_b32 s0, s38, 29
	s_add_i32 s0, s30, s0
	s_lshr_b32 s8, s2, 6
	s_ashr_i32 s1, s0, 3
	s_and_b32 s0, s0, -8
	s_lshr_b32 s3, s2, 8
	s_lshl_b32 s37, s8, 10
	s_sub_i32 s0, s30, s0
	s_cmp_lt_i32 s0, 0
	s_movk_i32 s39, 0x141
	s_cselect_b32 s4, s39, 0x140
	s_mul_i32 s0, s0, s4
	s_add_i32 s0, s0, s1
	s_ashr_i32 s1, s0, 31
	s_lshr_b32 s1, s1, 24
	s_add_i32 s1, s0, s1
	s_ashr_i32 s4, s1, 8
	s_and_b32 s1, s1, 0xffffff00
	s_sub_i32 s1, s0, s1
	s_sext_i32_i16 s0, s1
	s_bfe_u32 s0, s0, 0x3001c
	s_add_i32 s5, s1, s0
	s_sext_i32_i16 s0, s5
	s_and_b32 s5, s5, 0xfff8
	s_sub_i32 s1, s1, s5
	s_lshl_b32 s4, s4, 3
	s_sext_i32_i16 s1, s1
	s_lshr_b32 s0, s0, 3
	s_add_i32 s20, s4, s1
	v_and_b32_e32 v6, 32, v0
	s_ashr_i32 s21, s20, 31
	s_bfe_i64 s[6:7], s[0:1], 0x100000
	v_bitop3_b32 v11, v1, v6, 48 bitop3:0x6c
	v_and_b32_e32 v12, 64, v0
	s_lshl_b64 s[4:5], s[20:21], 19
	s_lshl_b64 s[6:7], s[6:7], 19
	v_lshrrev_b32_e32 v4, 2, v0
	v_or_b32_e32 v1, v11, v12
	s_add_u32 s24, s31, s6
	v_lshl_or_b32 v156, v3, 11, v1
	v_and_or_b32 v3, v4, 64, v5
	s_addc_u32 s25, s36, s7
	s_add_i32 s21, s37, 0
	v_lshl_or_b32 v160, v3, 11, v1
	s_add_i32 m0, s21, 0x10000
	v_lshl_or_b32 v158, v2, 11, v1
	global_load_lds_dwordx4 v160, s[24:25]
	s_add_i32 m0, s21, 0x12000
	s_add_u32 s6, s24, 0x4000
	global_load_lds_dwordx4 v156, s[24:25]
	s_addc_u32 s7, s25, 0
	s_add_i32 m0, s21, 0x14000
	v_lshrrev_b32_e32 v2, 3, v0
	global_load_lds_dwordx4 v160, s[6:7]
	s_add_i32 m0, s21, 0x16000
	s_add_u32 s22, s28, s4
	v_and_or_b32 v2, v2, 48, v13
	s_addc_u32 s23, s29, s5
	s_add_i32 s40, s21, 0x2000
	v_lshl_or_b32 v162, v2, 11, v1
	global_load_lds_dwordx4 v156, s[6:7]
	s_mov_b32 m0, s21
	s_add_u32 s4, s22, 0x40000
	global_load_lds_dwordx4 v162, s[22:23]
	s_mov_b32 m0, s40
	s_addc_u32 s5, s23, 0
	s_add_i32 s41, s21, 0x4000
	global_load_lds_dwordx4 v158, s[22:23]
	s_mov_b32 m0, s41
	s_add_i32 s42, s21, 0x6000
	global_load_lds_dwordx4 v162, s[4:5]
	s_mov_b32 m0, s42
	v_mov_b32_e32 v161, 0
	global_load_lds_dwordx4 v158, s[4:5]
	v_mov_b32_e32 v157, v161
	v_mov_b32_e32 v163, v161
	v_mov_b32_e32 v159, v161
	s_cmp_eq_u32 s3, 1
	s_mov_b32 s1, 0
	v_lshl_add_u64 v[8:9], s[24:25], 0, v[160:161]
	v_lshl_add_u64 v[6:7], s[24:25], 0, v[156:157]
	v_lshl_add_u64 v[2:3], s[22:23], 0, v[162:163]
	s_cselect_b64 s[4:5], -1, 0
	s_cmp_lg_u32 s3, 1
	v_lshl_add_u64 v[4:5], s[22:23], 0, v[158:159]
	s_cbranch_scc1 .LBB0_733
	s_barrier

.LBB0_800:
	s_cmp_lt_i32 s76, 9
	s_cselect_b64 s[0:1], -1, 0
	s_cmp_gt_i32 s77, 8
	s_cselect_b64 s[2:3], -1, 0
	s_and_b64 s[0:1], s[0:1], s[2:3]
	s_andn2_b64 vcc, exec, s[0:1]
	s_cbranch_vccnz .LBB0_900
	s_lshr_b32 s99, s30, 3
	s_and_b32 s99, s99, 7
